# NA epilogue: both d-blocks of a gate piece processed in lockstep (no back-to-back dependent VALU)
# baseline (speedup 1.0000x reference)
.Lna_dec_done_1:
	s_add_u32 s51, s50, 4
	s_mov_b32 s8, s4
	s_mov_b32 s9, s5
	s_lshl_b32 s6, s43, 8
	s_lshl_b32 s7, s4, 15
	s_add_u32 s7, s7, s6
	s_add_u32 s58, s26, s7
	s_addc_u32 s59, s27, 0
	s_lshl_b32 s7, s5, 15
	s_add_u32 s7, s7, s6
	s_add_u32 s60, s26, s7
	s_addc_u32 s61, s27, 0
	s_mul_i32 s7, s43, 0x744
	s_add_u32 s64, s24, s7
	s_addc_u32 s65, s25, 0
	global_load_dwordx4 v[64:67], v210, s[58:59]
	global_load_dwordx4 v[68:71], v210, s[58:59] offset:64
	global_load_dwordx4 v[72:75], v210, s[58:59] offset:128
	global_load_dwordx4 v[76:79], v210, s[58:59] offset:192
	global_load_dwordx4 v[80:83], v210, s[60:61]
	global_load_dwordx4 v[84:87], v210, s[60:61] offset:64
	global_load_dwordx4 v[88:91], v210, s[60:61] offset:128
	global_load_dwordx4 v[92:95], v210, s[60:61] offset:192
	global_load_dword v236, v213, s[64:65]
	s_mov_b32 s4, 0xbfb8aa3b
	s_mov_b32 s5, 0xbfb8aa3b
	ds_bpermute_b32 v224, v215, v220
	s_waitcnt lgkmcnt(0)
	v_add_f32_e32 v220, v220, v224
	ds_bpermute_b32 v224, v216, v220
	s_waitcnt lgkmcnt(0)
	v_add_f32_e32 v224, v220, v224
	v_mov_b32_e32 v225, v224
	s_waitcnt vmcnt(13)
	v_permlane16_swap_b32_e32 v96, v98
	v_permlane16_swap_b32_e32 v97, v99
	v_lshlrev_b32_e32 v226, 16, v96
	v_and_b32_e32 v227, 0xffff0000, v96
	v_lshlrev_b32_e32 v228, 16, v97
	v_and_b32_e32 v229, 0xffff0000, v97
	v_lshlrev_b32_e32 v112, 16, v98
	v_and_b32_e32 v113, 0xffff0000, v98
	v_lshlrev_b32_e32 v114, 16, v99
	v_and_b32_e32 v115, 0xffff0000, v99
	v_pk_mul_f32 v[230:231], v[226:227], s[4:5]
	v_pk_mul_f32 v[160:161], v[228:229], s[4:5]
	v_pk_mul_f32 v[116:117], v[112:113], s[4:5]
	v_pk_mul_f32 v[118:119], v[114:115], s[4:5]
	v_exp_f32_e32 v230, v230
	v_exp_f32_e32 v231, v231
	v_exp_f32_e32 v160, v160
	v_exp_f32_e32 v161, v161
	v_exp_f32_e32 v116, v116
	v_exp_f32_e32 v117, v117
	v_exp_f32_e32 v118, v118
	v_exp_f32_e32 v119, v119
	v_pk_mul_f32 v[0:1], v[0:1], v[226:227]
	v_pk_mul_f32 v[2:3], v[2:3], v[228:229]
	v_pk_mul_f32 v[4:5], v[4:5], v[112:113]
	v_pk_mul_f32 v[6:7], v[6:7], v[114:115]
	v_pk_fma_f32 v[230:231], v[230:231], v[224:225], v[224:225]
	v_pk_fma_f32 v[160:161], v[160:161], v[224:225], v[224:225]
	v_pk_fma_f32 v[116:117], v[116:117], v[224:225], v[224:225]
	v_pk_fma_f32 v[118:119], v[118:119], v[224:225], v[224:225]
	v_rcp_f32_e32 v230, v230
	v_rcp_f32_e32 v231, v231
	v_rcp_f32_e32 v160, v160
	v_rcp_f32_e32 v161, v161
	v_rcp_f32_e32 v116, v116
	v_rcp_f32_e32 v117, v117
	v_rcp_f32_e32 v118, v118
	v_rcp_f32_e32 v119, v119
	v_pk_mul_f32 v[0:1], v[0:1], v[230:231]
	v_pk_mul_f32 v[2:3], v[2:3], v[160:161]
	v_pk_mul_f32 v[4:5], v[4:5], v[116:117]
	v_pk_mul_f32 v[6:7], v[6:7], v[118:119]
	v_cvt_pk_bf16_f32 v0, v0, v1
	v_cvt_pk_bf16_f32 v1, v2, v3
	v_cvt_pk_bf16_f32 v2, v4, v5
	v_cvt_pk_bf16_f32 v3, v6, v7
	s_nop 1
	v_permlane16_swap_b32_e32 v0, v2
	v_permlane16_swap_b32_e32 v1, v3
	global_store_dwordx4 v212, v[0:3], s[12:13] offset:0
	v_permlane16_swap_b32_e32 v100, v102
	v_permlane16_swap_b32_e32 v101, v103
	v_lshlrev_b32_e32 v226, 16, v100
	v_and_b32_e32 v227, 0xffff0000, v100
	v_lshlrev_b32_e32 v228, 16, v101
	v_and_b32_e32 v229, 0xffff0000, v101
	v_lshlrev_b32_e32 v112, 16, v102
	v_and_b32_e32 v113, 0xffff0000, v102
	v_lshlrev_b32_e32 v114, 16, v103
	v_and_b32_e32 v115, 0xffff0000, v103
	v_pk_mul_f32 v[230:231], v[226:227], s[4:5]
	v_pk_mul_f32 v[160:161], v[228:229], s[4:5]
	v_pk_mul_f32 v[116:117], v[112:113], s[4:5]
	v_pk_mul_f32 v[118:119], v[114:115], s[4:5]
	v_exp_f32_e32 v230, v230
	v_exp_f32_e32 v231, v231
	v_exp_f32_e32 v160, v160
	v_exp_f32_e32 v161, v161
	v_exp_f32_e32 v116, v116
	v_exp_f32_e32 v117, v117
	v_exp_f32_e32 v118, v118
	v_exp_f32_e32 v119, v119
	v_pk_mul_f32 v[8:9], v[8:9], v[226:227]
	v_pk_mul_f32 v[10:11], v[10:11], v[228:229]
	v_pk_mul_f32 v[12:13], v[12:13], v[112:113]
	v_pk_mul_f32 v[14:15], v[14:15], v[114:115]
	v_pk_fma_f32 v[230:231], v[230:231], v[224:225], v[224:225]
	v_pk_fma_f32 v[160:161], v[160:161], v[224:225], v[224:225]
	v_pk_fma_f32 v[116:117], v[116:117], v[224:225], v[224:225]
	v_pk_fma_f32 v[118:119], v[118:119], v[224:225], v[224:225]
	v_rcp_f32_e32 v230, v230
	v_rcp_f32_e32 v231, v231
	v_rcp_f32_e32 v160, v160
	v_rcp_f32_e32 v161, v161
	v_rcp_f32_e32 v116, v116
	v_rcp_f32_e32 v117, v117
	v_rcp_f32_e32 v118, v118
	v_rcp_f32_e32 v119, v119
	v_pk_mul_f32 v[8:9], v[8:9], v[230:231]
	v_pk_mul_f32 v[10:11], v[10:11], v[160:161]
	v_pk_mul_f32 v[12:13], v[12:13], v[116:117]
	v_pk_mul_f32 v[14:15], v[14:15], v[118:119]
	v_cvt_pk_bf16_f32 v8, v8, v9
	v_cvt_pk_bf16_f32 v9, v10, v11
	v_cvt_pk_bf16_f32 v10, v12, v13
	v_cvt_pk_bf16_f32 v11, v14, v15
	s_nop 1
	v_permlane16_swap_b32_e32 v8, v10
	v_permlane16_swap_b32_e32 v9, v11
	global_store_dwordx4 v212, v[8:11], s[12:13] offset:64
	v_permlane16_swap_b32_e32 v104, v106
	v_permlane16_swap_b32_e32 v105, v107
	v_lshlrev_b32_e32 v226, 16, v104
	v_and_b32_e32 v227, 0xffff0000, v104
	v_lshlrev_b32_e32 v228, 16, v105
	v_and_b32_e32 v229, 0xffff0000, v105
	v_lshlrev_b32_e32 v112, 16, v106
	v_and_b32_e32 v113, 0xffff0000, v106
	v_lshlrev_b32_e32 v114, 16, v107
	v_and_b32_e32 v115, 0xffff0000, v107
	v_pk_mul_f32 v[230:231], v[226:227], s[4:5]
	v_pk_mul_f32 v[160:161], v[228:229], s[4:5]
	v_pk_mul_f32 v[116:117], v[112:113], s[4:5]
	v_pk_mul_f32 v[118:119], v[114:115], s[4:5]
	v_exp_f32_e32 v230, v230
	v_exp_f32_e32 v231, v231
	v_exp_f32_e32 v160, v160
	v_exp_f32_e32 v161, v161
	v_exp_f32_e32 v116, v116
	v_exp_f32_e32 v117, v117
	v_exp_f32_e32 v118, v118
	v_exp_f32_e32 v119, v119
	v_pk_mul_f32 v[16:17], v[16:17], v[226:227]
	v_pk_mul_f32 v[18:19], v[18:19], v[228:229]
	v_pk_mul_f32 v[20:21], v[20:21], v[112:113]
	v_pk_mul_f32 v[22:23], v[22:23], v[114:115]
	v_pk_fma_f32 v[230:231], v[230:231], v[224:225], v[224:225]
	v_pk_fma_f32 v[160:161], v[160:161], v[224:225], v[224:225]
	v_pk_fma_f32 v[116:117], v[116:117], v[224:225], v[224:225]
	v_pk_fma_f32 v[118:119], v[118:119], v[224:225], v[224:225]
	v_rcp_f32_e32 v230, v230
	v_rcp_f32_e32 v231, v231
	v_rcp_f32_e32 v160, v160
	v_rcp_f32_e32 v161, v161
	v_rcp_f32_e32 v116, v116
	v_rcp_f32_e32 v117, v117
	v_rcp_f32_e32 v118, v118
	v_rcp_f32_e32 v119, v119
	v_pk_mul_f32 v[16:17], v[16:17], v[230:231]
	v_pk_mul_f32 v[18:19], v[18:19], v[160:161]
	v_pk_mul_f32 v[20:21], v[20:21], v[116:117]
	v_pk_mul_f32 v[22:23], v[22:23], v[118:119]
	v_cvt_pk_bf16_f32 v16, v16, v17
	v_cvt_pk_bf16_f32 v17, v18, v19
	v_cvt_pk_bf16_f32 v18, v20, v21
	v_cvt_pk_bf16_f32 v19, v22, v23
	s_nop 1
	v_permlane16_swap_b32_e32 v16, v18
	v_permlane16_swap_b32_e32 v17, v19
	global_store_dwordx4 v212, v[16:19], s[12:13] offset:128
	v_permlane16_swap_b32_e32 v108, v110
	v_permlane16_swap_b32_e32 v109, v111
	v_lshlrev_b32_e32 v226, 16, v108
	v_and_b32_e32 v227, 0xffff0000, v108
	v_lshlrev_b32_e32 v228, 16, v109
	v_and_b32_e32 v229, 0xffff0000, v109
	v_lshlrev_b32_e32 v112, 16, v110
	v_and_b32_e32 v113, 0xffff0000, v110
	v_lshlrev_b32_e32 v114, 16, v111
	v_and_b32_e32 v115, 0xffff0000, v111
	v_pk_mul_f32 v[230:231], v[226:227], s[4:5]
	v_pk_mul_f32 v[160:161], v[228:229], s[4:5]
	v_pk_mul_f32 v[116:117], v[112:113], s[4:5]
	v_pk_mul_f32 v[118:119], v[114:115], s[4:5]
	v_exp_f32_e32 v230, v230
	v_exp_f32_e32 v231, v231
	v_exp_f32_e32 v160, v160
	v_exp_f32_e32 v161, v161
	v_exp_f32_e32 v116, v116
	v_exp_f32_e32 v117, v117
	v_exp_f32_e32 v118, v118
	v_exp_f32_e32 v119, v119
	v_pk_mul_f32 v[24:25], v[24:25], v[226:227]
	v_pk_mul_f32 v[26:27], v[26:27], v[228:229]
	v_pk_mul_f32 v[28:29], v[28:29], v[112:113]
	v_pk_mul_f32 v[30:31], v[30:31], v[114:115]
	v_pk_fma_f32 v[230:231], v[230:231], v[224:225], v[224:225]
	v_pk_fma_f32 v[160:161], v[160:161], v[224:225], v[224:225]
	v_pk_fma_f32 v[116:117], v[116:117], v[224:225], v[224:225]
	v_pk_fma_f32 v[118:119], v[118:119], v[224:225], v[224:225]
	v_rcp_f32_e32 v230, v230
	v_rcp_f32_e32 v231, v231
	v_rcp_f32_e32 v160, v160
	v_rcp_f32_e32 v161, v161
	v_rcp_f32_e32 v116, v116
	v_rcp_f32_e32 v117, v117
	v_rcp_f32_e32 v118, v118
	v_rcp_f32_e32 v119, v119
	v_pk_mul_f32 v[24:25], v[24:25], v[230:231]
	v_pk_mul_f32 v[26:27], v[26:27], v[160:161]
	v_pk_mul_f32 v[28:29], v[28:29], v[116:117]
	v_pk_mul_f32 v[30:31], v[30:31], v[118:119]
	v_cvt_pk_bf16_f32 v24, v24, v25
	v_cvt_pk_bf16_f32 v25, v26, v27
	v_cvt_pk_bf16_f32 v26, v28, v29
	v_cvt_pk_bf16_f32 v27, v30, v31
	s_nop 1
	v_permlane16_swap_b32_e32 v24, v26
	v_permlane16_swap_b32_e32 v25, v27
	global_store_dwordx4 v212, v[24:27], s[12:13] offset:192
	ds_bpermute_b32 v224, v215, v223
	s_waitcnt lgkmcnt(0)
	v_add_f32_e32 v223, v223, v224
	ds_bpermute_b32 v224, v216, v223
	s_waitcnt lgkmcnt(0)
	v_add_f32_e32 v224, v223, v224
	v_mov_b32_e32 v225, v224
	s_mov_b32 s52, 0
	s_cmp_lt_u32 s52, s50
	s_cbranch_scc0 .Lna_tb_ctx4
	s_add_u32 s1, s49, s52
	s_lshl_b32 s1, s1, 6
	s_lshl_b32 s2, s42, 11
	s_add_u32 s1, s1, s2
	s_branch .Lna_tb_done4

.Lna_tb_done4:
	s_lshl_b32 s1, s1, 15
	s_lshl_b32 s2, s43, 8
	s_add_u32 s1, s1, s2
	s_add_u32 s1, s1, 0x2000
	s_add_u32 s54, s26, s1
	s_addc_u32 s55, s27, 0
	s_add_u32 s56, s54, 0x2000
	s_addc_u32 s57, s55, 0
	global_load_dwordx4 v[96:99], v194, s[54:55]
	global_load_dwordx4 v[100:103], v194, s[56:57]
	global_load_dwordx4 v[104:107], v195, s[54:55]
	global_load_dwordx4 v[108:111], v195, s[56:57]
	s_waitcnt vmcnt(17)
	v_permlane16_swap_b32_e32 v128, v130
	v_permlane16_swap_b32_e32 v129, v131
	v_lshlrev_b32_e32 v226, 16, v128
	v_and_b32_e32 v227, 0xffff0000, v128
	v_lshlrev_b32_e32 v228, 16, v129
	v_and_b32_e32 v229, 0xffff0000, v129
	v_lshlrev_b32_e32 v112, 16, v130
	v_and_b32_e32 v113, 0xffff0000, v130
	v_lshlrev_b32_e32 v114, 16, v131
	v_and_b32_e32 v115, 0xffff0000, v131
	v_pk_mul_f32 v[230:231], v[226:227], s[4:5]
	v_pk_mul_f32 v[160:161], v[228:229], s[4:5]
	v_pk_mul_f32 v[116:117], v[112:113], s[4:5]
	v_pk_mul_f32 v[118:119], v[114:115], s[4:5]
	v_exp_f32_e32 v230, v230
	v_exp_f32_e32 v231, v231
	v_exp_f32_e32 v160, v160
	v_exp_f32_e32 v161, v161
	v_exp_f32_e32 v116, v116
	v_exp_f32_e32 v117, v117
	v_exp_f32_e32 v118, v118
	v_exp_f32_e32 v119, v119
	v_pk_mul_f32 v[32:33], v[32:33], v[226:227]
	v_pk_mul_f32 v[34:35], v[34:35], v[228:229]
	v_pk_mul_f32 v[36:37], v[36:37], v[112:113]
	v_pk_mul_f32 v[38:39], v[38:39], v[114:115]
	v_pk_fma_f32 v[230:231], v[230:231], v[224:225], v[224:225]
	v_pk_fma_f32 v[160:161], v[160:161], v[224:225], v[224:225]
	v_pk_fma_f32 v[116:117], v[116:117], v[224:225], v[224:225]
	v_pk_fma_f32 v[118:119], v[118:119], v[224:225], v[224:225]
	v_rcp_f32_e32 v230, v230
	v_rcp_f32_e32 v231, v231
	v_rcp_f32_e32 v160, v160
	v_rcp_f32_e32 v161, v161
	v_rcp_f32_e32 v116, v116
	v_rcp_f32_e32 v117, v117
	v_rcp_f32_e32 v118, v118
	v_rcp_f32_e32 v119, v119
	v_pk_mul_f32 v[32:33], v[32:33], v[230:231]
	v_pk_mul_f32 v[34:35], v[34:35], v[160:161]
	v_pk_mul_f32 v[36:37], v[36:37], v[116:117]
	v_pk_mul_f32 v[38:39], v[38:39], v[118:119]
	v_cvt_pk_bf16_f32 v32, v32, v33
	v_cvt_pk_bf16_f32 v33, v34, v35
	v_cvt_pk_bf16_f32 v34, v36, v37
	v_cvt_pk_bf16_f32 v35, v38, v39
	s_nop 1
	v_permlane16_swap_b32_e32 v32, v34
	v_permlane16_swap_b32_e32 v33, v35
	global_store_dwordx4 v212, v[32:35], s[30:31] offset:0
	v_permlane16_swap_b32_e32 v132, v134
	v_permlane16_swap_b32_e32 v133, v135
	v_lshlrev_b32_e32 v226, 16, v132
	v_and_b32_e32 v227, 0xffff0000, v132
	v_lshlrev_b32_e32 v228, 16, v133
	v_and_b32_e32 v229, 0xffff0000, v133
	v_lshlrev_b32_e32 v112, 16, v134
	v_and_b32_e32 v113, 0xffff0000, v134
	v_lshlrev_b32_e32 v114, 16, v135
	v_and_b32_e32 v115, 0xffff0000, v135
	v_pk_mul_f32 v[230:231], v[226:227], s[4:5]
	v_pk_mul_f32 v[160:161], v[228:229], s[4:5]
	v_pk_mul_f32 v[116:117], v[112:113], s[4:5]
	v_pk_mul_f32 v[118:119], v[114:115], s[4:5]
	v_exp_f32_e32 v230, v230
	v_exp_f32_e32 v231, v231
	v_exp_f32_e32 v160, v160
	v_exp_f32_e32 v161, v161
	v_exp_f32_e32 v116, v116
	v_exp_f32_e32 v117, v117
	v_exp_f32_e32 v118, v118
	v_exp_f32_e32 v119, v119
	v_pk_mul_f32 v[40:41], v[40:41], v[226:227]
	v_pk_mul_f32 v[42:43], v[42:43], v[228:229]
	v_pk_mul_f32 v[44:45], v[44:45], v[112:113]
	v_pk_mul_f32 v[46:47], v[46:47], v[114:115]
	v_pk_fma_f32 v[230:231], v[230:231], v[224:225], v[224:225]
	v_pk_fma_f32 v[160:161], v[160:161], v[224:225], v[224:225]
	v_pk_fma_f32 v[116:117], v[116:117], v[224:225], v[224:225]
	v_pk_fma_f32 v[118:119], v[118:119], v[224:225], v[224:225]
	v_rcp_f32_e32 v230, v230
	v_rcp_f32_e32 v231, v231
	v_rcp_f32_e32 v160, v160
	v_rcp_f32_e32 v161, v161
	v_rcp_f32_e32 v116, v116
	v_rcp_f32_e32 v117, v117
	v_rcp_f32_e32 v118, v118
	v_rcp_f32_e32 v119, v119
	v_pk_mul_f32 v[40:41], v[40:41], v[230:231]
	v_pk_mul_f32 v[42:43], v[42:43], v[160:161]
	v_pk_mul_f32 v[44:45], v[44:45], v[116:117]
	v_pk_mul_f32 v[46:47], v[46:47], v[118:119]
	v_cvt_pk_bf16_f32 v40, v40, v41
	v_cvt_pk_bf16_f32 v41, v42, v43
	v_cvt_pk_bf16_f32 v42, v44, v45
	v_cvt_pk_bf16_f32 v43, v46, v47
	s_nop 1
	v_permlane16_swap_b32_e32 v40, v42
	v_permlane16_swap_b32_e32 v41, v43
	global_store_dwordx4 v212, v[40:43], s[30:31] offset:64
	v_permlane16_swap_b32_e32 v136, v138
	v_permlane16_swap_b32_e32 v137, v139
	v_lshlrev_b32_e32 v226, 16, v136
	v_and_b32_e32 v227, 0xffff0000, v136
	v_lshlrev_b32_e32 v228, 16, v137
	v_and_b32_e32 v229, 0xffff0000, v137
	v_lshlrev_b32_e32 v112, 16, v138
	v_and_b32_e32 v113, 0xffff0000, v138
	v_lshlrev_b32_e32 v114, 16, v139
	v_and_b32_e32 v115, 0xffff0000, v139
	v_pk_mul_f32 v[230:231], v[226:227], s[4:5]
	v_pk_mul_f32 v[160:161], v[228:229], s[4:5]
	v_pk_mul_f32 v[116:117], v[112:113], s[4:5]
	v_pk_mul_f32 v[118:119], v[114:115], s[4:5]
	v_exp_f32_e32 v230, v230
	v_exp_f32_e32 v231, v231
	v_exp_f32_e32 v160, v160
	v_exp_f32_e32 v161, v161
	v_exp_f32_e32 v116, v116
	v_exp_f32_e32 v117, v117
	v_exp_f32_e32 v118, v118
	v_exp_f32_e32 v119, v119
	v_pk_mul_f32 v[48:49], v[48:49], v[226:227]
	v_pk_mul_f32 v[50:51], v[50:51], v[228:229]
	v_pk_mul_f32 v[52:53], v[52:53], v[112:113]
	v_pk_mul_f32 v[54:55], v[54:55], v[114:115]
	v_pk_fma_f32 v[230:231], v[230:231], v[224:225], v[224:225]
	v_pk_fma_f32 v[160:161], v[160:161], v[224:225], v[224:225]
	v_pk_fma_f32 v[116:117], v[116:117], v[224:225], v[224:225]
	v_pk_fma_f32 v[118:119], v[118:119], v[224:225], v[224:225]
	v_rcp_f32_e32 v230, v230
	v_rcp_f32_e32 v231, v231
	v_rcp_f32_e32 v160, v160
	v_rcp_f32_e32 v161, v161
	v_rcp_f32_e32 v116, v116
	v_rcp_f32_e32 v117, v117
	v_rcp_f32_e32 v118, v118
	v_rcp_f32_e32 v119, v119
	v_pk_mul_f32 v[48:49], v[48:49], v[230:231]
	v_pk_mul_f32 v[50:51], v[50:51], v[160:161]
	v_pk_mul_f32 v[52:53], v[52:53], v[116:117]
	v_pk_mul_f32 v[54:55], v[54:55], v[118:119]
	v_cvt_pk_bf16_f32 v48, v48, v49
	v_cvt_pk_bf16_f32 v49, v50, v51
	v_cvt_pk_bf16_f32 v50, v52, v53
	v_cvt_pk_bf16_f32 v51, v54, v55
	s_nop 1
	v_permlane16_swap_b32_e32 v48, v50
	v_permlane16_swap_b32_e32 v49, v51
	global_store_dwordx4 v212, v[48:51], s[30:31] offset:128
	v_permlane16_swap_b32_e32 v140, v142
	v_permlane16_swap_b32_e32 v141, v143
	v_lshlrev_b32_e32 v226, 16, v140
	v_and_b32_e32 v227, 0xffff0000, v140
	v_lshlrev_b32_e32 v228, 16, v141
	v_and_b32_e32 v229, 0xffff0000, v141
	v_lshlrev_b32_e32 v112, 16, v142
	v_and_b32_e32 v113, 0xffff0000, v142
	v_lshlrev_b32_e32 v114, 16, v143
	v_and_b32_e32 v115, 0xffff0000, v143
	v_pk_mul_f32 v[230:231], v[226:227], s[4:5]
	v_pk_mul_f32 v[160:161], v[228:229], s[4:5]
	v_pk_mul_f32 v[116:117], v[112:113], s[4:5]
	v_pk_mul_f32 v[118:119], v[114:115], s[4:5]
	v_exp_f32_e32 v230, v230
	v_exp_f32_e32 v231, v231
	v_exp_f32_e32 v160, v160
	v_exp_f32_e32 v161, v161
	v_exp_f32_e32 v116, v116
	v_exp_f32_e32 v117, v117
	v_exp_f32_e32 v118, v118
	v_exp_f32_e32 v119, v119
	v_pk_mul_f32 v[56:57], v[56:57], v[226:227]
	v_pk_mul_f32 v[58:59], v[58:59], v[228:229]
	v_pk_mul_f32 v[60:61], v[60:61], v[112:113]
	v_pk_mul_f32 v[62:63], v[62:63], v[114:115]
	v_pk_fma_f32 v[230:231], v[230:231], v[224:225], v[224:225]
	v_pk_fma_f32 v[160:161], v[160:161], v[224:225], v[224:225]
	v_pk_fma_f32 v[116:117], v[116:117], v[224:225], v[224:225]
	v_pk_fma_f32 v[118:119], v[118:119], v[224:225], v[224:225]
	v_rcp_f32_e32 v230, v230
	v_rcp_f32_e32 v231, v231
	v_rcp_f32_e32 v160, v160
	v_rcp_f32_e32 v161, v161
	v_rcp_f32_e32 v116, v116
	v_rcp_f32_e32 v117, v117
	v_rcp_f32_e32 v118, v118
	v_rcp_f32_e32 v119, v119
	v_pk_mul_f32 v[56:57], v[56:57], v[230:231]
	v_pk_mul_f32 v[58:59], v[58:59], v[160:161]
	v_pk_mul_f32 v[60:61], v[60:61], v[116:117]
	v_pk_mul_f32 v[62:63], v[62:63], v[118:119]
	v_cvt_pk_bf16_f32 v56, v56, v57
	v_cvt_pk_bf16_f32 v57, v58, v59
	v_cvt_pk_bf16_f32 v58, v60, v61
	v_cvt_pk_bf16_f32 v59, v62, v63
	s_nop 1
	v_permlane16_swap_b32_e32 v56, v58
	v_permlane16_swap_b32_e32 v57, v59
	global_store_dwordx4 v212, v[56:59], s[30:31] offset:192
	s_cmp_lt_u32 s15, s41
	s_cbranch_scc1 .Lna_unit_next
	s_branch .Lna_done
